# prompt attention fast loop: LDS address adds folded into ds_read offsets (11 VALU per tile pair), V-tile transposition with v_perm_b32 (8 VALU per tile)
# speedup vs baseline: 1.0487x; 1.0016x over previous
.LBB0_448:
	s_or_b64 exec, exec, s[34:35]
	s_xor_b64 s[34:35], s[20:21], -1
	s_and_b64 s[20:21], s[20:21], exec
	v_add_u32_e32 v6, 0x200, v2
	v_add_u32_e32 v14, 0x400, v2
	v_add_u32_e32 v16, 0x600, v2
	s_cselect_b32 s20, s63, s64
	v_ashrrev_i32_e32 v23, 4, v2
	v_ashrrev_i32_e32 v28, 4, v6
	v_ashrrev_i32_e32 v30, 4, v14
	v_ashrrev_i32_e32 v32, 4, v16
	s_lshl_b32 s38, s20, 7
	v_min_i32_e32 v4, 0x7f, v23
	v_min_i32_e32 v6, 0x7f, v28
	v_min_i32_e32 v14, 0x7f, v30
	v_min_i32_e32 v16, 0x7f, v32
	v_lshlrev_b32_e32 v0, 4, v2
	v_add_u32_e32 v4, s38, v4
	v_add_u32_e32 v6, s38, v6
	v_add_u32_e32 v14, s38, v14
	v_add_u32_e32 v16, s38, v16
	v_and_b32_e32 v0, 0xf0, v0
	v_ashrrev_i32_e32 v5, 31, v4
	v_ashrrev_i32_e32 v7, 31, v6
	v_ashrrev_i32_e32 v15, 31, v14
	v_ashrrev_i32_e32 v17, 31, v16
	v_lshl_add_u64 v[12:13], s[10:11], 0, v[0:1]
	v_lshlrev_b64 v[4:5], 11, v[4:5]
	v_lshlrev_b64 v[6:7], 11, v[6:7]
	v_lshlrev_b64 v[14:15], 11, v[14:15]
	v_lshlrev_b64 v[16:17], 11, v[16:17]
	v_lshl_add_u64 v[4:5], v[12:13], 0, v[4:5]
	v_lshl_add_u64 v[8:9], v[12:13], 0, v[6:7]
	v_lshl_add_u64 v[14:15], v[12:13], 0, v[14:15]
	v_lshl_add_u64 v[16:17], v[12:13], 0, v[16:17]
	global_load_dwordx4 v[4:7], v[4:5], off
	s_nop 0
	global_load_dwordx4 v[8:11], v[8:9], off
	s_nop 0
	global_load_dwordx4 v[12:15], v[14:15], off
	s_nop 0
	global_load_dwordx4 v[16:19], v[16:17], off
	v_ashrrev_i32_e32 v20, 3, v2
	v_ashrrev_i32_e32 v21, 31, v20
	v_lshlrev_b32_e32 v26, 5, v2
	s_add_i32 s20, 0, 0x11000
	v_lshlrev_b64 v[24:25], 11, v[20:21]
	v_add_u32_e32 v22, s20, v0
	v_and_b32_e32 v0, 0xe0, v26
	v_lshl_add_u64 v[24:25], s[12:13], 0, v[24:25]
	v_mad_u64_u32 v[26:27], s[20:21], v23, s51, v[22:23]
	v_lshl_add_u64 v[24:25], v[24:25], 0, v[0:1]
	v_mad_u64_u32 v[28:29], s[20:21], v28, s51, v[22:23]
	v_mad_u64_u32 v[30:31], s[20:21], v30, s51, v[22:23]
	v_mad_u64_u32 v[22:23], s[20:21], v32, s51, v[22:23]
	v_lshlrev_b32_e32 v3, 4, v3
	v_and_b32_e32 v165, 31, v2
	s_lshl_b32 s39, s65, 5
	s_ashr_i32 s40, s65, 2
	s_and_b32 s20, s39, 0x60
	v_or_b32_e32 v174, s20, v165
	s_lshl_b32 s41, s40, 7
	s_or_b32 s21, s38, 0x7f
	v_mov_b32_e32 v79, 0
	s_cmpk_lt_i32 s21, 0xffc1
	v_mov_b32_e32 v78, 0
	v_mov_b32_e32 v77, 0
	v_mov_b32_e32 v76, 0
	v_mov_b32_e32 v75, 0
	v_mov_b32_e32 v74, 0
	v_mov_b32_e32 v73, 0
	v_mov_b32_e32 v72, 0
	v_mov_b32_e32 v71, 0
	v_mov_b32_e32 v70, 0
	v_mov_b32_e32 v69, 0
	v_mov_b32_e32 v68, 0
	v_mov_b32_e32 v67, 0
	v_mov_b32_e32 v66, 0
	v_mov_b32_e32 v65, 0
	v_mov_b32_e32 v64, v79
	v_mov_b32_e32 v63, 0
	v_mov_b32_e32 v62, 0
	v_mov_b32_e32 v61, 0
	v_mov_b32_e32 v60, 0
	v_mov_b32_e32 v59, 0
	v_mov_b32_e32 v58, 0
	v_mov_b32_e32 v57, 0
	v_mov_b32_e32 v56, 0
	v_mov_b32_e32 v55, 0
	v_mov_b32_e32 v54, 0
	s_waitcnt vmcnt(3)
	ds_write_b128 v26, v[4:7]
	s_waitcnt vmcnt(2)
	ds_write_b128 v28, v[8:11]
	s_waitcnt vmcnt(1)
	ds_write_b128 v30, v[12:15]
	s_waitcnt vmcnt(0)
	ds_write_b128 v22, v[16:19]
	global_load_dwordx4 v[4:7], v[24:25], off
	global_load_dwordx4 v[8:11], v[24:25], off offset:16
	v_bfe_u32 v12, v2, 2, 4
	v_ashrrev_i32_e32 v14, 5, v2
	v_and_or_b32 v3, v3, 16, v12
	v_bfi_b32 v16, -4, v14, v2
	v_mov_b32_e32 v13, v1
	v_mul_lo_u32 v15, v20, s51
	v_lshlrev_b32_e32 v12, 12, v3
	v_lshlrev_b32_e32 v14, 3, v16
	v_add_u32_e32 v17, 0, v15
	v_lshl_add_u64 v[12:13], s[14:15], 0, v[12:13]
	v_ashrrev_i32_e32 v15, 31, v14
	v_add_u32_e32 v176, v17, v0
	v_lshl_add_u64 v[12:13], v[14:15], 1, v[12:13]
	v_bfe_u32 v0, v2, 5, 1
	v_mul_lo_u32 v2, v16, s56
	v_lshlrev_b32_e32 v3, 2, v3
	v_add_u32_e32 v2, 0, v2
	v_add_u32_e32 v177, v2, v3
	v_add_u32_e32 v178, 0x8800, v177
	v_lshl_add_u64 v[166:167], v[24:25], 0, s[4:5]
	v_lshlrev_b32_e32 v173, 4, v0
	v_lshlrev_b32_e32 v164, 3, v0
	v_mov_b32_e32 v53, 0
	v_mov_b32_e32 v52, 0
	v_mov_b32_e32 v51, 0
	v_mov_b32_e32 v50, 0
	v_mov_b32_e32 v49, 0
	v_mov_b32_e32 v48, v79
	v_mov_b32_e32 v47, 0
	v_mov_b32_e32 v46, 0
	v_mov_b32_e32 v45, 0
	v_mov_b32_e32 v44, 0
	v_mov_b32_e32 v43, 0
	v_mov_b32_e32 v42, 0
	v_mov_b32_e32 v41, 0
	v_mov_b32_e32 v40, 0
	v_mov_b32_e32 v39, 0
	v_mov_b32_e32 v38, 0
	v_mov_b32_e32 v37, 0
	v_mov_b32_e32 v36, 0
	v_mov_b32_e32 v35, 0
	v_mov_b32_e32 v34, 0
	v_mov_b32_e32 v33, 0
	v_mov_b32_e32 v32, v79
	v_mov_b32_e32 v31, 0
	v_mov_b32_e32 v30, 0
	v_mov_b32_e32 v29, 0
	v_mov_b32_e32 v28, 0
	v_mov_b32_e32 v27, 0
	v_mov_b32_e32 v26, 0
	v_mov_b32_e32 v25, 0
	s_waitcnt vmcnt(1)
	ds_write_b128 v176, v[4:7]
	s_waitcnt vmcnt(0)
	ds_write_b128 v176, v[8:11] offset:16
	global_load_dwordx4 v[4:7], v[12:13], off
	global_load_dwordx4 v[8:11], v[12:13], off offset:2048
	v_lshl_add_u64 v[168:169], v[12:13], 0, s[4:5]
	v_mov_b32_e32 v24, 0
	v_mov_b32_e32 v23, 0
	v_mov_b32_e32 v22, 0
	v_mov_b32_e32 v21, 0
	v_mov_b32_e32 v20, 0
	v_mov_b32_e32 v19, 0
	v_mov_b32_e32 v18, 0
	v_mov_b32_e32 v17, 0
	v_mov_b32_e32 v16, v79
	v_mov_b32_e32 v175, 0
	s_waitcnt vmcnt(1)
	v_and_b32_e32 v2, 0xffff, v4
	v_lshrrev_b32_e32 v3, 16, v4
	v_and_b32_e32 v4, 0xffff, v5
	v_lshrrev_b32_e32 v5, 16, v5
	v_and_b32_e32 v12, 0xffff, v6
	v_lshrrev_b32_e32 v6, 16, v6
	v_and_b32_e32 v13, 0xffff, v7
	v_lshrrev_b32_e32 v7, 16, v7
	s_waitcnt vmcnt(0)
	v_lshl_or_b32 v2, v8, 16, v2
	v_and_or_b32 v3, v8, s57, v3
	v_lshl_or_b32 v4, v9, 16, v4
	v_and_or_b32 v5, v9, s57, v5
	v_lshl_or_b32 v8, v10, 16, v12
	v_and_or_b32 v6, v10, s57, v6
	v_lshl_or_b32 v9, v11, 16, v13
	v_and_or_b32 v7, v11, s57, v7
	ds_write2_b32 v178, v2, v3 offset1:34
	ds_write2_b32 v178, v4, v5 offset0:68 offset1:102
	ds_write2_b32 v178, v8, v6 offset0:136 offset1:170
	ds_write2_b32 v178, v9, v7 offset0:204 offset1:238
	global_load_dwordx4 v[120:123], v[166:167], off offset:16
	global_load_dwordx4 v[124:127], v[166:167], off
	global_load_dwordx4 v[116:119], v[168:169], off
	global_load_dwordx4 v[112:115], v[168:169], off offset:2048
	v_mul_u32_u24_e32 v2, 0x110, v174
	v_or_b32_e32 v3, s41, v173
	v_add3_u32 v179, v3, v2, s50
	v_mul_u32_u24_e32 v2, 0x88, v165
	v_mul_u32_u24_e32 v3, 0x110, v165
	v_add3_u32 v2, v2, v164, s58
	v_add3_u32 v180, v173, v3, s41
	s_waitcnt lgkmcnt(0)
	s_barrier
	s_cbranch_scc1 .LBB0_465
	s_ashr_i32 s41, s21, 31
	v_lshlrev_b32_e32 v0, 2, v0
	s_lshr_b32 s41, s41, 26
	v_sub_u32_e32 v0, v0, v165
	s_add_i32 s21, s21, s41
	v_subrev_u32_e32 v0, s20, v0
	v_mov_b32_e32 v14, v1
	v_mov_b32_e32 v15, v1
	s_ashr_i32 s21, s21, 6
	s_or_b32 s42, s20, s38
	v_add_u32_e32 v181, 0, v2
	v_subrev_u32_e32 v182, s38, v0
	v_mov_b32_e32 v0, v1
	v_mov_b32_e32 v2, v1
	v_mov_b32_e32 v3, v1
	v_mov_b32_e32 v4, v1
	v_mov_b32_e32 v5, v1
	v_mov_b32_e32 v6, v1
	v_mov_b32_e32 v7, v1
	v_mov_b32_e32 v8, v1
	v_mov_b32_e32 v9, v1
	v_mov_b32_e32 v10, v1
	v_mov_b32_e32 v11, v1
	v_mov_b32_e32 v12, v1
	v_mov_b32_e32 v13, v1
	v_mov_b64_e32 v[30:31], v[14:15]
	v_mov_b64_e32 v[46:47], v[14:15]
	v_mov_b64_e32 v[62:63], v[14:15]
	v_mov_b64_e32 v[78:79], v[14:15]
	s_min_i32 s41, s21, 0xff
	s_ashr_i32 s43, s42, 6
	s_mov_b32 s44, 0
	v_mov_b32_e32 v175, 0
	s_movk_i32 s45, 0xda
	v_mov_b64_e32 v[28:29], v[12:13]
	v_mov_b64_e32 v[26:27], v[10:11]
	v_mov_b64_e32 v[24:25], v[8:9]
	v_mov_b64_e32 v[22:23], v[6:7]
	v_mov_b64_e32 v[20:21], v[4:5]
	v_mov_b64_e32 v[18:19], v[2:3]
	v_mov_b64_e32 v[16:17], v[0:1]
	v_mov_b64_e32 v[44:45], v[12:13]
	v_mov_b64_e32 v[42:43], v[10:11]
	v_mov_b64_e32 v[40:41], v[8:9]
	v_mov_b64_e32 v[38:39], v[6:7]
	v_mov_b64_e32 v[36:37], v[4:5]
	v_mov_b64_e32 v[34:35], v[2:3]
	v_mov_b64_e32 v[32:33], v[0:1]
	v_mov_b64_e32 v[60:61], v[12:13]
	v_mov_b64_e32 v[58:59], v[10:11]
	v_mov_b64_e32 v[56:57], v[8:9]
	v_mov_b64_e32 v[54:55], v[6:7]
	v_mov_b64_e32 v[52:53], v[4:5]
	v_mov_b64_e32 v[50:51], v[2:3]
	v_mov_b64_e32 v[48:49], v[0:1]
	v_mov_b64_e32 v[76:77], v[12:13]
	v_mov_b64_e32 v[74:75], v[10:11]
	v_mov_b64_e32 v[72:73], v[8:9]
	v_mov_b64_e32 v[70:71], v[6:7]
	v_mov_b64_e32 v[68:69], v[4:5]
	v_mov_b64_e32 v[66:67], v[2:3]
	v_mov_b64_e32 v[64:65], v[0:1]
	v_cmp_gt_f32_e32 vcc, 0xc2700000, v171
	s_cbranch_vccnz .LBB0_451
	s_mov_b32 s100, 0x05040100
	s_mov_b32 s101, 0x07060302
	s_branch .Lqf_451

.Lqf_451:
	v_lshl_add_u64 v[166:167], v[166:167], 0, s[4:5]
	v_lshl_add_u64 v[14:15], v[168:169], 0, s[4:5]
	global_load_dwordx4 v[10:13], v[166:167], off offset:16
	global_load_dwordx4 v[128:131], v[166:167], off
	global_load_dwordx4 v[2:5], v[14:15], off
	global_load_dwordx4 v[6:9], v[14:15], off offset:2048
	s_cmp_le_i32 s44, s43
	s_cselect_b64 s[20:21], -1, 0
	s_cmp_gt_i32 s44, s43
	s_cbranch_scc1 .Lqf_455
	ds_read_b128 v[80:83], v180
	ds_read_b128 v[96:99], v179
	ds_read_b128 v[132:135], v179 offset:32
	ds_read_b128 v[136:139], v180 offset:32
	ds_read_b128 v[100:103], v180 offset:8704
	ds_read_b128 v[140:143], v180 offset:8736
	s_sub_i32 s68, s45, 64
	s_cmp_le_i32 s68, s42
	s_waitcnt lgkmcnt(4)
	v_mfma_f32_32x32x16_bf16 v[80:95], v[80:83], v[96:99], 0
	s_waitcnt lgkmcnt(1)
	v_mfma_f32_32x32x16_bf16 v[96:111], v[100:103], v[96:99], 0
	v_mfma_f32_32x32x16_bf16 v[80:95], v[136:139], v[132:135], v[80:95]
	s_waitcnt lgkmcnt(0)
	v_mfma_f32_32x32x16_bf16 v[96:111], v[140:143], v[132:135], v[96:111]
	ds_read_b128 v[132:135], v180 offset:64
	ds_read_b128 v[136:139], v179 offset:64
	ds_read_b128 v[140:143], v179 offset:96
	ds_read_b128 v[144:147], v180 offset:96
	s_waitcnt lgkmcnt(2)
	v_mfma_f32_32x32x16_bf16 v[80:95], v[132:135], v[136:139], v[80:95]
	ds_read_b128 v[132:135], v180 offset:8768
	ds_read_b128 v[184:187], v180 offset:8800
	s_waitcnt lgkmcnt(1)
	v_mfma_f32_32x32x16_bf16 v[96:111], v[132:135], v[136:139], v[96:111]
	v_mfma_f32_32x32x16_bf16 v[80:95], v[144:147], v[140:143], v[80:95]
	s_waitcnt lgkmcnt(0)
	v_mfma_f32_32x32x16_bf16 v[96:111], v[184:187], v[140:143], v[96:111]
	s_cbranch_scc1 .Lqf_454
	v_add_u32_e32 v0, s45, v182
	v_add_u32_e32 v134, 0xffffff27, v0
	s_add_i32 s68, 0, 0x19800
	v_max_i32_e32 v134, 0xffffff80, v134
	v_lshl_add_u32 v136, v134, 2, s68
	v_add_u32_e32 v134, 0xffffff28, v0
	v_add_u32_e32 v132, 0xffffff26, v0
	v_add_u32_e32 v133, 0xffffff46, v0
	v_add_u32_e32 v135, 0xffffff47, v0
	v_add_u32_e32 v137, 0xffffff48, v0
	v_max_i32_e32 v134, 0xffffff80, v134
	v_add_u32_e32 v139, 0xffffff49, v0
	v_max_i32_e32 v132, 0xffffff80, v132
	v_max_i32_e32 v133, 0xffffff80, v133
	v_max_i32_e32 v135, 0xffffff80, v135
	v_max_i32_e32 v137, 0xffffff80, v137
	v_lshl_add_u32 v138, v134, 2, s68
	v_add_u32_e32 v134, 0xffffff29, v0
	v_max_i32_e32 v139, 0xffffff80, v139
	v_lshl_add_u32 v132, v132, 2, s68
	v_lshl_add_u32 v133, v133, 2, s68
	v_lshl_add_u32 v135, v135, 2, s68
	v_lshl_add_u32 v137, v137, 2, s68
	v_max_i32_e32 v134, 0xffffff80, v134
	v_lshl_add_u32 v139, v139, 2, s68
	v_lshl_add_u32 v140, v134, 2, s68
	ds_read_b32 v132, v132 offset:512
	ds_read_b32 v134, v133 offset:512
	ds_read_b32 v133, v136 offset:512
	ds_read_b32 v135, v135 offset:512
	ds_read_b32 v136, v138 offset:512
	ds_read_b32 v138, v137 offset:512
	ds_read_b32 v137, v140 offset:512
	ds_read_b32 v139, v139 offset:512
	v_add_u32_e32 v142, 0xffffff2f, v0
	v_max_i32_e32 v142, 0xffffff80, v142
	v_lshl_add_u32 v144, v142, 2, s68
	v_add_u32_e32 v142, 0xffffff30, v0
	v_add_u32_e32 v140, 0xffffff2e, v0
	v_add_u32_e32 v141, 0xffffff4e, v0
	v_add_u32_e32 v143, 0xffffff4f, v0
	v_add_u32_e32 v145, 0xffffff50, v0
	v_max_i32_e32 v142, 0xffffff80, v142
	v_add_u32_e32 v147, 0xffffff51, v0
	v_max_i32_e32 v140, 0xffffff80, v140
	v_max_i32_e32 v141, 0xffffff80, v141
	v_max_i32_e32 v143, 0xffffff80, v143
	v_max_i32_e32 v145, 0xffffff80, v145
	v_lshl_add_u32 v146, v142, 2, s68
	v_add_u32_e32 v142, 0xffffff31, v0
	v_max_i32_e32 v147, 0xffffff80, v147
	v_lshl_add_u32 v140, v140, 2, s68
	v_lshl_add_u32 v141, v141, 2, s68
	v_lshl_add_u32 v143, v143, 2, s68
	v_lshl_add_u32 v145, v145, 2, s68
	v_max_i32_e32 v142, 0xffffff80, v142
	v_lshl_add_u32 v147, v147, 2, s68
	v_lshl_add_u32 v168, v142, 2, s68
	ds_read_b32 v140, v140 offset:512
	ds_read_b32 v142, v141 offset:512
	ds_read_b32 v141, v144 offset:512
	ds_read_b32 v143, v143 offset:512
	ds_read_b32 v144, v146 offset:512
	ds_read_b32 v146, v145 offset:512
	ds_read_b32 v145, v168 offset:512
	ds_read_b32 v147, v147 offset:512
	v_add_u32_e32 v184, 0xffffff57, v0
	v_max_i32_e32 v184, 0xffffff80, v184
	v_lshl_add_u32 v185, v184, 2, s68
	v_add_u32_e32 v184, 0xffffff38, v0
	v_add_u32_e32 v186, 0xffffff58, v0
	v_max_i32_e32 v184, 0xffffff80, v184
	v_add_u32_e32 v168, 0xffffff36, v0
	v_add_u32_e32 v169, 0xffffff56, v0
	v_max_i32_e32 v186, 0xffffff80, v186
	v_lshl_add_u32 v187, v184, 2, s68
	v_add_u32_e32 v184, 0xffffff39, v0
	v_max_i32_e32 v168, 0xffffff80, v168
	v_max_i32_e32 v169, 0xffffff80, v169
	v_add_u32_e32 v183, 0xffffff37, v0
	v_lshl_add_u32 v188, v186, 2, s68
	v_add_u32_e32 v186, 0xffffff59, v0
	v_max_i32_e32 v184, 0xffffff80, v184
	v_lshl_add_u32 v168, v168, 2, s68
	v_lshl_add_u32 v169, v169, 2, s68
	v_max_i32_e32 v183, 0xffffff80, v183
	v_max_i32_e32 v186, 0xffffff80, v186
	v_lshl_add_u32 v189, v184, 2, s68
	v_lshl_add_u32 v183, v183, 2, s68
	v_lshl_add_u32 v190, v186, 2, s68
	ds_read_b32 v168, v168 offset:512
	ds_read_b32 v184, v169 offset:512
	ds_read_b32 v169, v183 offset:512
	ds_read_b32 v185, v185 offset:512
	ds_read_b32 v186, v187 offset:512
	ds_read_b32 v188, v188 offset:512
	ds_read_b32 v187, v189 offset:512
	ds_read_b32 v189, v190 offset:512
	v_add_u32_e32 v183, 0xffffff3e, v0
	v_add_u32_e32 v190, 0xffffff5e, v0
	v_max_i32_e32 v183, 0xffffff80, v183
	v_add_u32_e32 v191, 0xffffff3f, v0
	v_add_u32_e32 v192, 0xffffff5f, v0
	v_add_u32_e32 v193, 0xffffff40, v0
	v_add_u32_e32 v196, 0xffffff60, v0
	v_add_u32_e32 v197, 0xffffff41, v0
	v_add_u32_e32 v0, 0xffffff61, v0
	v_max_i32_e32 v190, 0xffffff80, v190
	v_lshl_add_u32 v183, v183, 2, s68
	v_max_i32_e32 v191, 0xffffff80, v191
	v_max_i32_e32 v192, 0xffffff80, v192
	v_max_i32_e32 v193, 0xffffff80, v193
	v_max_i32_e32 v196, 0xffffff80, v196
	v_max_i32_e32 v197, 0xffffff80, v197
	v_max_i32_e32 v0, 0xffffff80, v0
	v_lshl_add_u32 v190, v190, 2, s68
	v_lshl_add_u32 v191, v191, 2, s68
	v_lshl_add_u32 v192, v192, 2, s68
	v_lshl_add_u32 v193, v193, 2, s68
	v_lshl_add_u32 v196, v196, 2, s68
	v_lshl_add_u32 v197, v197, 2, s68
	s_waitcnt lgkmcnt(14)
	v_pk_add_f32 v[82:83], v[82:83], v[136:137]
	v_pk_add_f32 v[80:81], v[80:81], v[132:133]
	s_waitcnt lgkmcnt(9)
	v_pk_add_f32 v[86:87], v[86:87], v[144:145]
	v_pk_add_f32 v[84:85], v[84:85], v[140:141]
	v_lshl_add_u32 v0, v0, 2, s68
	ds_read_b32 v132, v183 offset:512
	ds_read_b32 v136, v190 offset:512
	ds_read_b32 v140, v193 offset:512
	ds_read_b32 v141, v197 offset:512
	ds_read_b32 v133, v191 offset:512
	ds_read_b32 v137, v192 offset:512
	ds_read_b32 v144, v196 offset:512
	ds_read_b32 v145, v0 offset:512
	s_waitcnt lgkmcnt(9)
	v_pk_add_f32 v[90:91], v[90:91], v[186:187]
	v_pk_add_f32 v[88:89], v[88:89], v[168:169]
	s_waitcnt lgkmcnt(4)
	v_pk_add_f32 v[94:95], v[94:95], v[140:141]
	s_waitcnt lgkmcnt(3)
	v_pk_add_f32 v[92:93], v[92:93], v[132:133]
	v_pk_add_f32 v[98:99], v[98:99], v[138:139]
	v_pk_add_f32 v[96:97], v[96:97], v[134:135]
	v_pk_add_f32 v[102:103], v[102:103], v[146:147]
	v_pk_add_f32 v[100:101], v[100:101], v[142:143]
	v_pk_add_f32 v[106:107], v[106:107], v[188:189]
	v_pk_add_f32 v[104:105], v[104:105], v[184:185]
	s_waitcnt lgkmcnt(0)
	v_pk_add_f32 v[110:111], v[110:111], v[144:145]
	v_pk_add_f32 v[108:109], v[108:109], v[136:137]

.Lqf_455:
	s_andn2_b64 vcc, exec, s[20:21]
	s_waitcnt vmcnt(6)
	ds_write_b128 v176, v[124:127] offset:17408
	ds_write_b128 v176, v[120:123] offset:17424
	s_cbranch_vccnz .Lqf_457
	ds_read_b64 v[80:81], v181
	ds_read_b64 v[82:83], v181 offset:16
	ds_read_b64 v[84:85], v181 offset:32
	ds_read_b64 v[86:87], v181 offset:48
	ds_read_b64 v[88:89], v181 offset:64
	ds_read_b64 v[90:91], v181 offset:80
	ds_read_b64 v[92:93], v181 offset:96
	ds_read_b64 v[94:95], v181 offset:112
	s_waitcnt lgkmcnt(6)
	v_mfma_f32_32x32x16_bf16 v[64:79], v[80:83], v[132:135], v[64:79]
	s_waitcnt lgkmcnt(4)
	v_mfma_f32_32x32x16_bf16 v[64:79], v[84:87], v[140:143], v[64:79]
	ds_read_b64 v[80:81], v181 offset:4352
	ds_read_b64 v[82:83], v181 offset:4368
	ds_read_b64 v[84:85], v181 offset:4384
	ds_read_b64 v[86:87], v181 offset:4400
	s_waitcnt lgkmcnt(6)
	v_mfma_f32_32x32x16_bf16 v[64:79], v[88:91], v[136:139], v[64:79]
	s_waitcnt lgkmcnt(4)
	v_mfma_f32_32x32x16_bf16 v[64:79], v[92:95], v[144:147], v[64:79]
	ds_read_b64 v[88:89], v181 offset:4416
	ds_read_b64 v[90:91], v181 offset:4432
	ds_read_b64 v[92:93], v181 offset:4448
	ds_read_b64 v[94:95], v181 offset:4464
	s_waitcnt lgkmcnt(6)
	v_mfma_f32_32x32x16_bf16 v[48:63], v[80:83], v[132:135], v[48:63]
	s_waitcnt lgkmcnt(4)
	v_mfma_f32_32x32x16_bf16 v[48:63], v[84:87], v[140:143], v[48:63]
	ds_read_b64 v[80:81], v181 offset:8704
	ds_read_b64 v[82:83], v181 offset:8720
	ds_read_b64 v[84:85], v181 offset:8736
	ds_read_b64 v[86:87], v181 offset:8752
	s_waitcnt lgkmcnt(6)
	v_mfma_f32_32x32x16_bf16 v[48:63], v[88:91], v[136:139], v[48:63]
	s_waitcnt lgkmcnt(4)
	v_mfma_f32_32x32x16_bf16 v[48:63], v[92:95], v[144:147], v[48:63]
	ds_read_b64 v[88:89], v181 offset:8768
	ds_read_b64 v[90:91], v181 offset:8784
	ds_read_b64 v[92:93], v181 offset:8800
	ds_read_b64 v[94:95], v181 offset:8816
	s_waitcnt lgkmcnt(6)
	v_mfma_f32_32x32x16_bf16 v[32:47], v[80:83], v[132:135], v[32:47]
	s_waitcnt lgkmcnt(4)
	v_mfma_f32_32x32x16_bf16 v[32:47], v[84:87], v[140:143], v[32:47]
	ds_read_b64 v[80:81], v181 offset:13056
	ds_read_b64 v[82:83], v181 offset:13072
	ds_read_b64 v[84:85], v181 offset:13088
	ds_read_b64 v[86:87], v181 offset:13104
	s_waitcnt lgkmcnt(6)
	v_mfma_f32_32x32x16_bf16 v[32:47], v[88:91], v[136:139], v[32:47]
	s_waitcnt lgkmcnt(4)
	v_mfma_f32_32x32x16_bf16 v[32:47], v[92:95], v[144:147], v[32:47]
	ds_read_b64 v[88:89], v181 offset:13120
	ds_read_b64 v[90:91], v181 offset:13136
	ds_read_b64 v[92:93], v181 offset:13152
	ds_read_b64 v[94:95], v181 offset:13168
	s_waitcnt lgkmcnt(6)
	v_mfma_f32_32x32x16_bf16 v[16:31], v[80:83], v[132:135], v[16:31]
	s_waitcnt lgkmcnt(4)
	v_mfma_f32_32x32x16_bf16 v[16:31], v[84:87], v[140:143], v[16:31]
	s_waitcnt lgkmcnt(2)
	v_mfma_f32_32x32x16_bf16 v[16:31], v[88:91], v[136:139], v[16:31]
	s_waitcnt lgkmcnt(0)
	v_mfma_f32_32x32x16_bf16 v[16:31], v[92:95], v[144:147], v[16:31]
.Lqf_457:
	s_waitcnt vmcnt(5)
	s_waitcnt vmcnt(4)
	v_perm_b32 v0, v112, v116, s100
	v_perm_b32 v80, v112, v116, s101
	v_add_u32_e32 v81, 0xcc00, v177
	ds_write2_b32 v81, v0, v80 offset1:34
	v_perm_b32 v0, v113, v117, s100
	v_perm_b32 v80, v113, v117, s101
	ds_write2_b32 v81, v0, v80 offset0:68 offset1:102
	v_perm_b32 v0, v114, v118, s100
	v_perm_b32 v80, v114, v118, s101
	ds_write2_b32 v81, v0, v80 offset0:136 offset1:170
	v_perm_b32 v0, v115, v119, s100
	v_perm_b32 v80, v115, v119, s101
	s_mov_b64 s[20:21], -1
	s_cmp_ge_i32 s44, s41
	v_readfirstlane_b32 s69, v0
	v_readfirstlane_b32 s68, v0
	ds_write2_b32 v81, v0, v80 offset0:204 offset1:238
	s_waitcnt lgkmcnt(0)
	s_barrier
	s_cbranch_scc1 .Lqf_450
	v_lshl_add_u64 v[166:167], v[166:167], 0, s[4:5]
	v_lshl_add_u64 v[168:169], v[14:15], 0, s[4:5]
	global_load_dwordx4 v[120:123], v[166:167], off offset:16
	global_load_dwordx4 v[124:127], v[166:167], off
	global_load_dwordx4 v[116:119], v[168:169], off
	global_load_dwordx4 v[112:115], v[168:169], off offset:2048
	s_cmp_lt_i32 s44, s43
	s_cselect_b64 s[20:21], -1, 0
	s_cmp_ge_i32 s44, s43
	s_cbranch_scc1 .Lqf_462
	ds_read_b128 v[80:83], v180 offset:17408
	ds_read_b128 v[96:99], v179
	ds_read_b128 v[148:151], v179 offset:32
	ds_read_b128 v[152:155], v180 offset:17440
	ds_read_b128 v[100:103], v180 offset:26112
	ds_read_b128 v[156:159], v180 offset:26144
	s_cmp_le_i32 s45, s42
	s_waitcnt lgkmcnt(4)
	v_mfma_f32_32x32x16_bf16 v[80:95], v[80:83], v[96:99], 0
	s_waitcnt lgkmcnt(1)
	v_mfma_f32_32x32x16_bf16 v[96:111], v[100:103], v[96:99], 0
	v_mfma_f32_32x32x16_bf16 v[80:95], v[152:155], v[148:151], v[80:95]
	s_waitcnt lgkmcnt(0)
	v_mfma_f32_32x32x16_bf16 v[96:111], v[156:159], v[148:151], v[96:111]
	ds_read_b128 v[148:151], v180 offset:17472
	ds_read_b128 v[152:155], v179 offset:64
	ds_read_b128 v[156:159], v179 offset:96
	ds_read_b128 v[160:163], v180 offset:17504
	s_waitcnt lgkmcnt(2)
	v_mfma_f32_32x32x16_bf16 v[80:95], v[148:151], v[152:155], v[80:95]
	ds_read_b128 v[148:151], v180 offset:26176
	ds_read_b128 v[184:187], v180 offset:26208
	s_waitcnt lgkmcnt(1)
	v_mfma_f32_32x32x16_bf16 v[96:111], v[148:151], v[152:155], v[96:111]
	v_mfma_f32_32x32x16_bf16 v[80:95], v[160:163], v[156:159], v[80:95]
	s_waitcnt lgkmcnt(0)
	v_mfma_f32_32x32x16_bf16 v[96:111], v[184:187], v[156:159], v[96:111]
	s_cbranch_scc1 .Lqf_461
	v_add_u32_e32 v0, s45, v182
	v_add_u32_e32 v148, 0xffffff67, v0
	s_add_i32 s68, 0, 0x19800
	v_max_i32_e32 v148, 0xffffff80, v148
	v_lshl_add_u32 v150, v148, 2, s68
	v_add_u32_e32 v148, 0xffffff68, v0
	v_add_u32_e32 v14, 0xffffff66, v0
	v_add_u32_e32 v15, 0xffffff86, v0
	v_add_u32_e32 v149, 0xffffff87, v0
	v_add_u32_e32 v151, 0xffffff88, v0
	v_max_i32_e32 v148, 0xffffff80, v148
	v_add_u32_e32 v153, 0xffffff89, v0
	v_max_i32_e32 v14, 0xffffff80, v14
	v_max_i32_e32 v15, 0xffffff80, v15
	v_max_i32_e32 v149, 0xffffff80, v149
	v_max_i32_e32 v151, 0xffffff80, v151
	v_lshl_add_u32 v152, v148, 2, s68
	v_add_u32_e32 v148, 0xffffff69, v0
	v_max_i32_e32 v153, 0xffffff80, v153
	v_lshl_add_u32 v14, v14, 2, s68
	v_lshl_add_u32 v15, v15, 2, s68
	v_lshl_add_u32 v149, v149, 2, s68
	v_lshl_add_u32 v151, v151, 2, s68
	v_max_i32_e32 v148, 0xffffff80, v148
	v_lshl_add_u32 v153, v153, 2, s68
	v_lshl_add_u32 v154, v148, 2, s68
	ds_read_b32 v14, v14 offset:512
	ds_read_b32 v148, v15 offset:512
	ds_read_b32 v15, v150 offset:512
	ds_read_b32 v149, v149 offset:512
	ds_read_b32 v150, v152 offset:512
	ds_read_b32 v152, v151 offset:512
	ds_read_b32 v151, v154 offset:512
	ds_read_b32 v153, v153 offset:512
	v_add_u32_e32 v156, 0xffffff6f, v0
	v_max_i32_e32 v156, 0xffffff80, v156
	v_lshl_add_u32 v158, v156, 2, s68
	v_add_u32_e32 v156, 0xffffff70, v0
	v_add_u32_e32 v154, 0xffffff6e, v0
	v_add_u32_e32 v155, 0xffffff8e, v0
	v_add_u32_e32 v157, 0xffffff8f, v0
	v_add_u32_e32 v159, 0xffffff90, v0
	v_max_i32_e32 v156, 0xffffff80, v156
	v_add_u32_e32 v161, 0xffffff91, v0
	v_max_i32_e32 v154, 0xffffff80, v154
	v_max_i32_e32 v155, 0xffffff80, v155
	v_max_i32_e32 v157, 0xffffff80, v157
	v_max_i32_e32 v159, 0xffffff80, v159
	v_lshl_add_u32 v160, v156, 2, s68
	v_add_u32_e32 v156, 0xffffff71, v0
	v_max_i32_e32 v161, 0xffffff80, v161
	v_lshl_add_u32 v154, v154, 2, s68
	v_lshl_add_u32 v155, v155, 2, s68
	v_lshl_add_u32 v157, v157, 2, s68
	v_lshl_add_u32 v159, v159, 2, s68
	v_max_i32_e32 v156, 0xffffff80, v156
	v_lshl_add_u32 v161, v161, 2, s68
	v_lshl_add_u32 v162, v156, 2, s68
	ds_read_b32 v154, v154 offset:512
	ds_read_b32 v156, v155 offset:512
	ds_read_b32 v155, v158 offset:512
	ds_read_b32 v157, v157 offset:512
	ds_read_b32 v158, v160 offset:512
	ds_read_b32 v160, v159 offset:512
	ds_read_b32 v159, v162 offset:512
	ds_read_b32 v161, v161 offset:512
	v_add_u32_e32 v184, 0xffffff97, v0
	v_max_i32_e32 v184, 0xffffff80, v184
	v_lshl_add_u32 v185, v184, 2, s68
	v_add_u32_e32 v184, 0xffffff78, v0
	v_add_u32_e32 v186, 0xffffff98, v0
	v_max_i32_e32 v184, 0xffffff80, v184
	v_add_u32_e32 v162, 0xffffff76, v0
	v_add_u32_e32 v163, 0xffffff96, v0
	v_max_i32_e32 v186, 0xffffff80, v186
	v_lshl_add_u32 v187, v184, 2, s68
	v_add_u32_e32 v184, 0xffffff79, v0
	v_max_i32_e32 v162, 0xffffff80, v162
	v_max_i32_e32 v163, 0xffffff80, v163
	v_add_u32_e32 v183, 0xffffff77, v0
	v_lshl_add_u32 v188, v186, 2, s68
	v_add_u32_e32 v186, 0xffffff99, v0
	v_max_i32_e32 v184, 0xffffff80, v184
	v_lshl_add_u32 v162, v162, 2, s68
	v_lshl_add_u32 v163, v163, 2, s68
	v_max_i32_e32 v183, 0xffffff80, v183
	v_max_i32_e32 v186, 0xffffff80, v186
	v_lshl_add_u32 v189, v184, 2, s68
	v_lshl_add_u32 v183, v183, 2, s68
	v_lshl_add_u32 v190, v186, 2, s68
	ds_read_b32 v162, v162 offset:512
	ds_read_b32 v184, v163 offset:512
	ds_read_b32 v163, v183 offset:512
	ds_read_b32 v185, v185 offset:512
	ds_read_b32 v186, v187 offset:512
	ds_read_b32 v188, v188 offset:512
	ds_read_b32 v187, v189 offset:512
	ds_read_b32 v189, v190 offset:512
	v_add_u32_e32 v183, 0xffffff7e, v0
	v_add_u32_e32 v190, 0xffffff9e, v0
	v_max_i32_e32 v183, 0xffffff80, v183
	v_add_u32_e32 v191, 0xffffff7f, v0
	v_add_u32_e32 v192, 0xffffff9f, v0
	v_add_u32_e32 v193, 0xffffff80, v0
	v_add_u32_e32 v196, 0xffffffa0, v0
	v_add_u32_e32 v197, 0xffffff81, v0
	v_add_u32_e32 v0, 0xffffffa1, v0
	v_max_i32_e32 v190, 0xffffff80, v190
	v_lshl_add_u32 v183, v183, 2, s68
	v_max_i32_e32 v191, 0xffffff80, v191
	v_max_i32_e32 v192, 0xffffff80, v192
	v_max_i32_e32 v193, 0xffffff80, v193
	v_max_i32_e32 v196, 0xffffff80, v196
	v_max_i32_e32 v197, 0xffffff80, v197
	v_max_i32_e32 v0, 0xffffff80, v0
	v_lshl_add_u32 v190, v190, 2, s68
	v_lshl_add_u32 v191, v191, 2, s68
	v_lshl_add_u32 v192, v192, 2, s68
	v_lshl_add_u32 v193, v193, 2, s68
	v_lshl_add_u32 v196, v196, 2, s68
	v_lshl_add_u32 v197, v197, 2, s68
	s_waitcnt lgkmcnt(14)
	v_pk_add_f32 v[82:83], v[82:83], v[150:151]
	v_pk_add_f32 v[80:81], v[80:81], v[14:15]
	s_waitcnt lgkmcnt(9)
	v_pk_add_f32 v[86:87], v[86:87], v[158:159]
	v_pk_add_f32 v[84:85], v[84:85], v[154:155]
	v_lshl_add_u32 v0, v0, 2, s68
	ds_read_b32 v14, v183 offset:512
	ds_read_b32 v150, v190 offset:512
	ds_read_b32 v154, v193 offset:512
	ds_read_b32 v155, v197 offset:512
	ds_read_b32 v15, v191 offset:512
	ds_read_b32 v151, v192 offset:512
	ds_read_b32 v158, v196 offset:512
	ds_read_b32 v159, v0 offset:512
	s_waitcnt lgkmcnt(9)
	v_pk_add_f32 v[90:91], v[90:91], v[186:187]
	v_pk_add_f32 v[88:89], v[88:89], v[162:163]
	s_waitcnt lgkmcnt(4)
	v_pk_add_f32 v[94:95], v[94:95], v[154:155]
	s_waitcnt lgkmcnt(3)
	v_pk_add_f32 v[92:93], v[92:93], v[14:15]
	v_pk_add_f32 v[98:99], v[98:99], v[152:153]
	v_pk_add_f32 v[96:97], v[96:97], v[148:149]
	v_pk_add_f32 v[102:103], v[102:103], v[160:161]
	v_pk_add_f32 v[100:101], v[100:101], v[156:157]
	v_pk_add_f32 v[106:107], v[106:107], v[188:189]
	v_pk_add_f32 v[104:105], v[104:105], v[184:185]
	s_waitcnt lgkmcnt(0)
	v_pk_add_f32 v[110:111], v[110:111], v[158:159]
	v_pk_add_f32 v[108:109], v[108:109], v[150:151]

.Lqf_462:
	s_andn2_b64 vcc, exec, s[20:21]
	s_waitcnt vmcnt(6)
	ds_write_b128 v176, v[128:131]
	ds_write_b128 v176, v[10:13] offset:16
	s_cbranch_vccnz .Lqf_464
	ds_read_b64 v[10:11], v181 offset:17408
	ds_read_b64 v[12:13], v181 offset:17424
	ds_read_b64 v[80:81], v181 offset:17440
	ds_read_b64 v[82:83], v181 offset:17456
	ds_read_b64 v[84:85], v181 offset:17472
	ds_read_b64 v[86:87], v181 offset:17488
	ds_read_b64 v[88:89], v181 offset:17504
	ds_read_b64 v[90:91], v181 offset:17520
	s_waitcnt lgkmcnt(6)
	v_mfma_f32_32x32x16_bf16 v[64:79], v[10:13], v[148:151], v[64:79]
	s_waitcnt lgkmcnt(4)
	v_mfma_f32_32x32x16_bf16 v[64:79], v[80:83], v[156:159], v[64:79]
	ds_read_b64 v[10:11], v181 offset:21760
	ds_read_b64 v[12:13], v181 offset:21776
	ds_read_b64 v[80:81], v181 offset:21792
	ds_read_b64 v[82:83], v181 offset:21808
	s_waitcnt lgkmcnt(6)
	v_mfma_f32_32x32x16_bf16 v[64:79], v[84:87], v[152:155], v[64:79]
	s_waitcnt lgkmcnt(4)
	v_mfma_f32_32x32x16_bf16 v[64:79], v[88:91], v[160:163], v[64:79]
	ds_read_b64 v[84:85], v181 offset:21824
	ds_read_b64 v[86:87], v181 offset:21840
	ds_read_b64 v[88:89], v181 offset:21856
	ds_read_b64 v[90:91], v181 offset:21872
	s_waitcnt lgkmcnt(6)
	v_mfma_f32_32x32x16_bf16 v[48:63], v[10:13], v[148:151], v[48:63]
	s_waitcnt lgkmcnt(4)
	v_mfma_f32_32x32x16_bf16 v[48:63], v[80:83], v[156:159], v[48:63]
	ds_read_b64 v[10:11], v181 offset:26112
	ds_read_b64 v[12:13], v181 offset:26128
	ds_read_b64 v[80:81], v181 offset:26144
	ds_read_b64 v[82:83], v181 offset:26160
	s_waitcnt lgkmcnt(6)
	v_mfma_f32_32x32x16_bf16 v[48:63], v[84:87], v[152:155], v[48:63]
	s_waitcnt lgkmcnt(4)
	v_mfma_f32_32x32x16_bf16 v[48:63], v[88:91], v[160:163], v[48:63]
	ds_read_b64 v[84:85], v181 offset:26176
	ds_read_b64 v[86:87], v181 offset:26192
	ds_read_b64 v[88:89], v181 offset:26208
	ds_read_b64 v[90:91], v181 offset:26224
	s_waitcnt lgkmcnt(6)
	v_mfma_f32_32x32x16_bf16 v[32:47], v[10:13], v[148:151], v[32:47]
	s_waitcnt lgkmcnt(4)
	v_mfma_f32_32x32x16_bf16 v[32:47], v[80:83], v[156:159], v[32:47]
	ds_read_b64 v[10:11], v181 offset:30464
	ds_read_b64 v[12:13], v181 offset:30480
	ds_read_b64 v[80:81], v181 offset:30496
	ds_read_b64 v[82:83], v181 offset:30512
	s_waitcnt lgkmcnt(6)
	v_mfma_f32_32x32x16_bf16 v[32:47], v[84:87], v[152:155], v[32:47]
	s_waitcnt lgkmcnt(4)
	v_mfma_f32_32x32x16_bf16 v[32:47], v[88:91], v[160:163], v[32:47]
	ds_read_b64 v[84:85], v181 offset:30528
	ds_read_b64 v[86:87], v181 offset:30544
	ds_read_b64 v[88:89], v181 offset:30560
	ds_read_b64 v[90:91], v181 offset:30576
	s_waitcnt lgkmcnt(6)
	v_mfma_f32_32x32x16_bf16 v[16:31], v[10:13], v[148:151], v[16:31]
	s_waitcnt lgkmcnt(4)
	v_mfma_f32_32x32x16_bf16 v[16:31], v[80:83], v[156:159], v[16:31]
	s_waitcnt lgkmcnt(2)
	v_mfma_f32_32x32x16_bf16 v[16:31], v[84:87], v[152:155], v[16:31]
	s_waitcnt lgkmcnt(0)
	v_mfma_f32_32x32x16_bf16 v[16:31], v[88:91], v[160:163], v[16:31]
.Lqf_464:
	s_waitcnt vmcnt(5)
	s_waitcnt vmcnt(4)
	v_perm_b32 v0, v6, v2, s100
	v_perm_b32 v2, v6, v2, s101
	ds_write2_b32 v178, v0, v2 offset1:34
	v_perm_b32 v0, v7, v3, s100
	v_perm_b32 v2, v7, v3, s101
	ds_write2_b32 v178, v0, v2 offset0:68 offset1:102
	v_perm_b32 v0, v8, v4, s100
	v_perm_b32 v2, v8, v4, s101
	s_add_i32 s44, s44, 2
	ds_write2_b32 v178, v0, v2 offset0:136 offset1:170
	v_perm_b32 v0, v9, v5, s100
	v_perm_b32 v2, v9, v5, s101
	s_addk_i32 s45, 0x80
	s_cmp_gt_i32 s44, s41
	ds_write2_b32 v178, v0, v2 offset0:204 offset1:238
	s_waitcnt lgkmcnt(0)
	s_barrier
	s_cselect_b64 s[20:21], -1, 0
	s_and_b64 vcc, exec, s[20:21]
	s_cbranch_vccz .Lqf_451
